# code placement: .p2align 6 on the heads of the four big GEMM K-loops (P8, P9, P18, P19)
# baseline (speedup 1.0000x reference)
; template <class Epi, bool ALIGN_EPI>
; __device__ __forceinline__ void gemm_phase(LAS unsigned char* lds, const Gemm g, const StaticOrder& S, const Epi& E) {
;     ...
;         const bool has_next = S.next(ui + 1, nxt);
;         const char* nA = has_next ? (const char*)g.A + (size_t)nxt.pm * tA + (size_t)nxt.pn * g.acol : cA; const char* nB = has_next ? (const char*)g.Bt + (size_t)nxt.pn * tB : cB;
;         for (int t = 0; t < nt; t += 2) {
;             const bool last = (t == nt - 2);
;             const char* a1 = cA + (size_t)(t + 1) * kstep;
;             const char* a2 = last ? nA : cA + (size_t)(t + 2) * kstep; const char* b2 = last ? nB : cB + (size_t)(t + 2) * kstep;
;             const char* a3 = a2 + kstep; const char* b3 = b2 + kstep;
;     ...
; #pragma unroll
;         for (int a = 0; a < 2; ++a)
; #pragma unroll
;             for (int b = 0; b < 2; ++b)
; #pragma unroll
;                 for (int m = 0; m < 4; ++m)
; #pragma unroll
;                     for (int n = 0; n < 2; ++n) acc[a][b][m][n] = (f32x4){0.f, 0.f, 0.f, 0.f};
.LBB0_925:
	s_ashr_i32 s47, s46, 31
	s_lshl_b64 s[48:49], s[46:47], 20
	s_add_u32 s48, s0, s48
	s_addc_u32 s49, s1, s49
	s_and_b64 s[50:51], s[4:5], exec
	s_cselect_b32 s47, s49, s7
	s_cselect_b32 s67, s48, s6
	s_ashr_i32 s45, s44, 31
	s_lshl_b64 s[50:51], s[44:45], 20
	s_add_u32 s50, s2, s50
	s_addc_u32 s51, s3, s51
	s_and_b64 s[54:55], s[4:5], exec
	s_cselect_b32 s45, s51, s9
	s_cselect_b32 s68, s50, s8
	s_add_u32 s6, s6, 0x80080
	s_addc_u32 s7, s7, 0
	s_add_u32 s69, s8, 0x100
	v_mov_b32_e32 v0, 0
	s_addc_u32 s70, s9, 0
	s_mov_b32 s71, -2
	v_mov_b32_e32 v1, v0
	v_mov_b32_e32 v2, v0
	v_mov_b32_e32 v3, v0
	v_mov_b32_e32 v4, v0
	v_mov_b32_e32 v5, v0
	v_mov_b32_e32 v6, v0
	v_mov_b32_e32 v7, v0
	v_mov_b32_e32 v16, v0
	v_mov_b32_e32 v17, v0
	v_mov_b32_e32 v18, v0
	v_mov_b32_e32 v19, v0
	v_mov_b32_e32 v20, v0
	v_mov_b32_e32 v21, v0
	v_mov_b32_e32 v22, v0
	v_mov_b32_e32 v23, v0
	v_mov_b32_e32 v32, v0
	v_mov_b32_e32 v33, v0
	v_mov_b32_e32 v34, v0
	v_mov_b32_e32 v35, v0
	v_mov_b32_e32 v36, v0
	v_mov_b32_e32 v37, v0
	v_mov_b32_e32 v38, v0
	v_mov_b32_e32 v39, v0
	v_mov_b32_e32 v48, v0
	v_mov_b32_e32 v49, v0
	v_mov_b32_e32 v50, v0
	v_mov_b32_e32 v51, v0
	v_mov_b32_e32 v52, v0
	v_mov_b32_e32 v53, v0
	v_mov_b32_e32 v54, v0
	v_mov_b32_e32 v55, v0
	v_mov_b32_e32 v8, v0
	v_mov_b32_e32 v9, v0
	v_mov_b32_e32 v10, v0
	v_mov_b32_e32 v11, v0
	v_mov_b32_e32 v12, v0
	v_mov_b32_e32 v13, v0
	v_mov_b32_e32 v14, v0
	v_mov_b32_e32 v15, v0
	v_mov_b32_e32 v24, v0
	v_mov_b32_e32 v25, v0
	v_mov_b32_e32 v26, v0
	v_mov_b32_e32 v27, v0
	v_mov_b32_e32 v28, v0
	v_mov_b32_e32 v29, v0
	v_mov_b32_e32 v30, v0
	v_mov_b32_e32 v31, v0
	v_mov_b32_e32 v40, v0
	v_mov_b32_e32 v41, v0
	v_mov_b32_e32 v42, v0
	v_mov_b32_e32 v43, v0
	v_mov_b32_e32 v44, v0
	v_mov_b32_e32 v45, v0
	v_mov_b32_e32 v46, v0
	v_mov_b32_e32 v47, v0
	v_mov_b32_e32 v56, v0
	v_mov_b32_e32 v57, v0
	v_mov_b32_e32 v58, v0
	v_mov_b32_e32 v59, v0
	v_mov_b32_e32 v60, v0
	v_mov_b32_e32 v61, v0
	v_mov_b32_e32 v62, v0
	v_mov_b32_e32 v63, v0
	v_mov_b32_e32 v64, v0
	v_mov_b32_e32 v65, v0
	v_mov_b32_e32 v66, v0
	v_mov_b32_e32 v67, v0
	v_mov_b32_e32 v68, v0
	v_mov_b32_e32 v69, v0
	v_mov_b32_e32 v70, v0
	v_mov_b32_e32 v71, v0
	v_mov_b32_e32 v80, v0
	v_mov_b32_e32 v81, v0
	v_mov_b32_e32 v82, v0
	v_mov_b32_e32 v83, v0
	v_mov_b32_e32 v84, v0
	v_mov_b32_e32 v85, v0
	v_mov_b32_e32 v86, v0
	v_mov_b32_e32 v87, v0
	v_mov_b32_e32 v96, v0
	v_mov_b32_e32 v97, v0
	v_mov_b32_e32 v98, v0
	v_mov_b32_e32 v99, v0
	v_mov_b32_e32 v100, v0
	v_mov_b32_e32 v101, v0
	v_mov_b32_e32 v102, v0
	v_mov_b32_e32 v103, v0
	v_mov_b32_e32 v112, v0
	v_mov_b32_e32 v113, v0
	v_mov_b32_e32 v114, v0
	v_mov_b32_e32 v115, v0
	v_mov_b32_e32 v116, v0
	v_mov_b32_e32 v117, v0
	v_mov_b32_e32 v118, v0
	v_mov_b32_e32 v119, v0
	v_mov_b32_e32 v72, v0
	v_mov_b32_e32 v73, v0
	v_mov_b32_e32 v74, v0
	v_mov_b32_e32 v75, v0
	v_mov_b32_e32 v76, v0
	v_mov_b32_e32 v77, v0
	v_mov_b32_e32 v78, v0
	v_mov_b32_e32 v79, v0
	v_mov_b32_e32 v88, v0
	v_mov_b32_e32 v89, v0
	v_mov_b32_e32 v90, v0
	v_mov_b32_e32 v91, v0
	v_mov_b32_e32 v92, v0
	v_mov_b32_e32 v93, v0
	v_mov_b32_e32 v94, v0
	v_mov_b32_e32 v95, v0
	v_mov_b32_e32 v104, v0
	v_mov_b32_e32 v105, v0
	v_mov_b32_e32 v106, v0
	v_mov_b32_e32 v107, v0
	v_mov_b32_e32 v108, v0
	v_mov_b32_e32 v109, v0
	v_mov_b32_e32 v110, v0
	v_mov_b32_e32 v111, v0
	v_mov_b32_e32 v120, v0
	v_mov_b32_e32 v121, v0
	v_mov_b32_e32 v122, v0
	v_mov_b32_e32 v123, v0
	v_mov_b32_e32 v124, v0
	v_mov_b32_e32 v125, v0
	v_mov_b32_e32 v126, v0
	v_mov_b32_e32 v127, v0
	.p2align	6

; template <class Epi, bool ALIGN_EPI>
; __device__ __forceinline__ void gemm_phase(LAS unsigned char* lds, const Gemm g, const StaticOrder& S, const Epi& E) {
;     ...
;         const bool has_next = S.next(ui + 1, nxt);
;         const char* nA = has_next ? (const char*)g.A + (size_t)nxt.pm * tA + (size_t)nxt.pn * g.acol : cA; const char* nB = has_next ? (const char*)g.Bt + (size_t)nxt.pn * tB : cB;
;         for (int t = 0; t < nt; t += 2) {
;             const bool last = (t == nt - 2);
;             const char* a1 = cA + (size_t)(t + 1) * kstep;
;             const char* a2 = last ? nA : cA + (size_t)(t + 2) * kstep; const char* b2 = last ? nB : cB + (size_t)(t + 2) * kstep;
;             const char* a3 = a2 + kstep; const char* b3 = b2 + kstep;
;     ...
; #pragma unroll
;         for (int a = 0; a < 2; ++a)
; #pragma unroll
;             for (int b = 0; b < 2; ++b)
; #pragma unroll
;                 for (int m = 0; m < 4; ++m)
; #pragma unroll
;                     for (int n = 0; n < 2; ++n) acc[a][b][m][n] = (f32x4){0.f, 0.f, 0.f, 0.f};
.LBB0_1004:
	s_ashr_i32 s25, s24, 31
	s_lshl_b64 s[26:27], s[24:25], 22
	s_add_u32 s26, s2, s26
	s_addc_u32 s27, s3, s27
	s_and_b64 s[28:29], s[6:7], exec
	s_cselect_b32 s25, s27, s37
	s_cselect_b32 s31, s26, s36
	s_ashr_i32 s23, s22, 31
	s_lshl_b64 s[28:29], s[22:23], 22
	s_add_u32 s28, s0, s28
	s_addc_u32 s29, s1, s29
	s_and_b64 s[42:43], s[6:7], exec
	s_cselect_b32 s23, s29, s41
	s_cselect_b32 s54, s28, s40
	s_add_u32 s36, s36, 0x200080
	s_addc_u32 s37, s37, 0
	s_add_u32 s55, s40, 0x100
	v_mov_b32_e32 v0, 0
	s_addc_u32 s56, s41, 0
	s_mov_b32 s57, -2
	s_waitcnt lgkmcnt(0)
	v_mov_b32_e32 v1, v0
	v_mov_b32_e32 v2, v0
	v_mov_b32_e32 v3, v0
	v_mov_b32_e32 v4, v0
	v_mov_b32_e32 v5, v0
	v_mov_b32_e32 v6, v0
	v_mov_b32_e32 v7, v0
	v_mov_b32_e32 v16, v0
	v_mov_b32_e32 v17, v0
	v_mov_b32_e32 v18, v0
	v_mov_b32_e32 v19, v0
	v_mov_b32_e32 v20, v0
	v_mov_b32_e32 v21, v0
	v_mov_b32_e32 v22, v0
	v_mov_b32_e32 v23, v0
	v_mov_b32_e32 v32, v0
	v_mov_b32_e32 v33, v0
	v_mov_b32_e32 v34, v0
	v_mov_b32_e32 v35, v0
	v_mov_b32_e32 v36, v0
	v_mov_b32_e32 v37, v0
	v_mov_b32_e32 v38, v0
	v_mov_b32_e32 v39, v0
	v_mov_b32_e32 v48, v0
	v_mov_b32_e32 v49, v0
	v_mov_b32_e32 v50, v0
	v_mov_b32_e32 v51, v0
	v_mov_b32_e32 v52, v0
	v_mov_b32_e32 v53, v0
	v_mov_b32_e32 v54, v0
	v_mov_b32_e32 v55, v0
	v_mov_b32_e32 v8, v0
	v_mov_b32_e32 v9, v0
	v_mov_b32_e32 v10, v0
	v_mov_b32_e32 v11, v0
	v_mov_b32_e32 v12, v0
	v_mov_b32_e32 v13, v0
	v_mov_b32_e32 v14, v0
	v_mov_b32_e32 v15, v0
	v_mov_b32_e32 v24, v0
	v_mov_b32_e32 v25, v0
	v_mov_b32_e32 v26, v0
	v_mov_b32_e32 v27, v0
	v_mov_b32_e32 v28, v0
	v_mov_b32_e32 v29, v0
	v_mov_b32_e32 v30, v0
	v_mov_b32_e32 v31, v0
	v_mov_b32_e32 v40, v0
	v_mov_b32_e32 v41, v0
	v_mov_b32_e32 v42, v0
	v_mov_b32_e32 v43, v0
	v_mov_b32_e32 v44, v0
	v_mov_b32_e32 v45, v0
	v_mov_b32_e32 v46, v0
	v_mov_b32_e32 v47, v0
	v_mov_b32_e32 v56, v0
	v_mov_b32_e32 v57, v0
	v_mov_b32_e32 v58, v0
	v_mov_b32_e32 v59, v0
	v_mov_b32_e32 v60, v0
	v_mov_b32_e32 v61, v0
	v_mov_b32_e32 v62, v0
	v_mov_b32_e32 v63, v0
	v_mov_b32_e32 v64, v0
	v_mov_b32_e32 v65, v0
	v_mov_b32_e32 v66, v0
	v_mov_b32_e32 v67, v0
	v_mov_b32_e32 v68, v0
	v_mov_b32_e32 v69, v0
	v_mov_b32_e32 v70, v0
	v_mov_b32_e32 v71, v0
	v_mov_b32_e32 v80, v0
	v_mov_b32_e32 v81, v0
	v_mov_b32_e32 v82, v0
	v_mov_b32_e32 v83, v0
	v_mov_b32_e32 v84, v0
	v_mov_b32_e32 v85, v0
	v_mov_b32_e32 v86, v0
	v_mov_b32_e32 v87, v0
	v_mov_b32_e32 v96, v0
	v_mov_b32_e32 v97, v0
	v_mov_b32_e32 v98, v0
	v_mov_b32_e32 v99, v0
	v_mov_b32_e32 v100, v0
	v_mov_b32_e32 v101, v0
	v_mov_b32_e32 v102, v0
	v_mov_b32_e32 v103, v0
	v_mov_b32_e32 v108, v0
	v_mov_b32_e32 v109, v0
	v_mov_b32_e32 v110, v0
	v_mov_b32_e32 v111, v0
	v_mov_b32_e32 v116, v0
	v_mov_b32_e32 v117, v0
	v_mov_b32_e32 v118, v0
	v_mov_b32_e32 v119, v0
	v_mov_b32_e32 v72, v0
	v_mov_b32_e32 v73, v0
	v_mov_b32_e32 v74, v0
	v_mov_b32_e32 v75, v0
	v_mov_b32_e32 v76, v0
	v_mov_b32_e32 v77, v0
	v_mov_b32_e32 v78, v0
	v_mov_b32_e32 v79, v0
	v_mov_b32_e32 v88, v0
	v_mov_b32_e32 v89, v0
	v_mov_b32_e32 v90, v0
	v_mov_b32_e32 v91, v0
	v_mov_b32_e32 v92, v0
	v_mov_b32_e32 v93, v0
	v_mov_b32_e32 v94, v0
	v_mov_b32_e32 v95, v0
	v_mov_b32_e32 v104, v0
	v_mov_b32_e32 v105, v0
	v_mov_b32_e32 v106, v0
	v_mov_b32_e32 v107, v0
	v_mov_b32_e32 v112, v0
	v_mov_b32_e32 v113, v0
	v_mov_b32_e32 v114, v0
	v_mov_b32_e32 v115, v0
	v_mov_b32_e32 v120, v0
	v_mov_b32_e32 v121, v0
	v_mov_b32_e32 v122, v0
	v_mov_b32_e32 v123, v0
	v_mov_b32_e32 v124, v0
	v_mov_b32_e32 v125, v0
	v_mov_b32_e32 v126, v0
	v_mov_b32_e32 v127, v0
	.p2align	6

; template <class Epi, bool ALIGN_EPI>
; __device__ __forceinline__ void gemm_phase(LAS unsigned char* lds, const Gemm g, const StaticOrder& S, const Epi& E) {
;     ...
;         const bool has_next = S.next(ui + 1, nxt);
;         const char* nA = has_next ? (const char*)g.A + (size_t)nxt.pm * tA + (size_t)nxt.pn * g.acol : cA; const char* nB = has_next ? (const char*)g.Bt + (size_t)nxt.pn * tB : cB;
;         for (int t = 0; t < nt; t += 2) {
;             const bool last = (t == nt - 2);
;             const char* a1 = cA + (size_t)(t + 1) * kstep;
;             const char* a2 = last ? nA : cA + (size_t)(t + 2) * kstep; const char* b2 = last ? nB : cB + (size_t)(t + 2) * kstep;
;             const char* a3 = a2 + kstep; const char* b3 = b2 + kstep;
;     ...
; #pragma unroll
;         for (int a = 0; a < 2; ++a)
; #pragma unroll
;             for (int b = 0; b < 2; ++b)
; #pragma unroll
;                 for (int m = 0; m < 4; ++m)
; #pragma unroll
;                     for (int n = 0; n < 2; ++n) acc[a][b][m][n] = (f32x4){0.f, 0.f, 0.f, 0.f};
.LBB0_1675:
	s_ashr_i32 s47, s46, 31
	s_lshl_b64 s[48:49], s[46:47], 20
	s_add_u32 s48, s2, s48
	s_addc_u32 s49, s3, s49
	s_and_b64 s[50:51], s[4:5], exec
	s_cselect_b32 s47, s49, s7
	s_cselect_b32 s67, s48, s6
	s_ashr_i32 s45, s44, 31
	s_lshl_b64 s[50:51], s[44:45], 20
	s_add_u32 s50, s0, s50
	s_addc_u32 s51, s1, s51
	s_and_b64 s[54:55], s[4:5], exec
	s_cselect_b32 s45, s51, s9
	s_cselect_b32 s68, s50, s8
	s_add_u32 s6, s6, 0x80080
	s_addc_u32 s7, s7, 0
	s_add_u32 s69, s8, 0x100
	v_mov_b32_e32 v0, 0
	s_addc_u32 s70, s9, 0
	s_mov_b32 s71, -2
	v_mov_b32_e32 v1, v0
	v_mov_b32_e32 v2, v0
	v_mov_b32_e32 v3, v0
	v_mov_b32_e32 v4, v0
	v_mov_b32_e32 v5, v0
	v_mov_b32_e32 v6, v0
	v_mov_b32_e32 v7, v0
	v_mov_b32_e32 v16, v0
	v_mov_b32_e32 v17, v0
	v_mov_b32_e32 v18, v0
	v_mov_b32_e32 v19, v0
	v_mov_b32_e32 v20, v0
	v_mov_b32_e32 v21, v0
	v_mov_b32_e32 v22, v0
	v_mov_b32_e32 v23, v0
	v_mov_b32_e32 v32, v0
	v_mov_b32_e32 v33, v0
	v_mov_b32_e32 v34, v0
	v_mov_b32_e32 v35, v0
	v_mov_b32_e32 v36, v0
	v_mov_b32_e32 v37, v0
	v_mov_b32_e32 v38, v0
	v_mov_b32_e32 v39, v0
	v_mov_b32_e32 v48, v0
	v_mov_b32_e32 v49, v0
	v_mov_b32_e32 v50, v0
	v_mov_b32_e32 v51, v0
	v_mov_b32_e32 v52, v0
	v_mov_b32_e32 v53, v0
	v_mov_b32_e32 v54, v0
	v_mov_b32_e32 v55, v0
	v_mov_b32_e32 v8, v0
	v_mov_b32_e32 v9, v0
	v_mov_b32_e32 v10, v0
	v_mov_b32_e32 v11, v0
	v_mov_b32_e32 v12, v0
	v_mov_b32_e32 v13, v0
	v_mov_b32_e32 v14, v0
	v_mov_b32_e32 v15, v0
	v_mov_b32_e32 v24, v0
	v_mov_b32_e32 v25, v0
	v_mov_b32_e32 v26, v0
	v_mov_b32_e32 v27, v0
	v_mov_b32_e32 v28, v0
	v_mov_b32_e32 v29, v0
	v_mov_b32_e32 v30, v0
	v_mov_b32_e32 v31, v0
	v_mov_b32_e32 v40, v0
	v_mov_b32_e32 v41, v0
	v_mov_b32_e32 v42, v0
	v_mov_b32_e32 v43, v0
	v_mov_b32_e32 v44, v0
	v_mov_b32_e32 v45, v0
	v_mov_b32_e32 v46, v0
	v_mov_b32_e32 v47, v0
	v_mov_b32_e32 v56, v0
	v_mov_b32_e32 v57, v0
	v_mov_b32_e32 v58, v0
	v_mov_b32_e32 v59, v0
	v_mov_b32_e32 v60, v0
	v_mov_b32_e32 v61, v0
	v_mov_b32_e32 v62, v0
	v_mov_b32_e32 v63, v0
	v_mov_b32_e32 v64, v0
	v_mov_b32_e32 v65, v0
	v_mov_b32_e32 v66, v0
	v_mov_b32_e32 v67, v0
	v_mov_b32_e32 v68, v0
	v_mov_b32_e32 v69, v0
	v_mov_b32_e32 v70, v0
	v_mov_b32_e32 v71, v0
	v_mov_b32_e32 v80, v0
	v_mov_b32_e32 v81, v0
	v_mov_b32_e32 v82, v0
	v_mov_b32_e32 v83, v0
	v_mov_b32_e32 v84, v0
	v_mov_b32_e32 v85, v0
	v_mov_b32_e32 v86, v0
	v_mov_b32_e32 v87, v0
	v_mov_b32_e32 v96, v0
	v_mov_b32_e32 v97, v0
	v_mov_b32_e32 v98, v0
	v_mov_b32_e32 v99, v0
	v_mov_b32_e32 v100, v0
	v_mov_b32_e32 v101, v0
	v_mov_b32_e32 v102, v0
	v_mov_b32_e32 v103, v0
	v_mov_b32_e32 v112, v0
	v_mov_b32_e32 v113, v0
	v_mov_b32_e32 v114, v0
	v_mov_b32_e32 v115, v0
	v_mov_b32_e32 v116, v0
	v_mov_b32_e32 v117, v0
	v_mov_b32_e32 v118, v0
	v_mov_b32_e32 v119, v0
	v_mov_b32_e32 v72, v0
	v_mov_b32_e32 v73, v0
	v_mov_b32_e32 v74, v0
	v_mov_b32_e32 v75, v0
	v_mov_b32_e32 v76, v0
	v_mov_b32_e32 v77, v0
	v_mov_b32_e32 v78, v0
	v_mov_b32_e32 v79, v0
	v_mov_b32_e32 v88, v0
	v_mov_b32_e32 v89, v0
	v_mov_b32_e32 v90, v0
	v_mov_b32_e32 v91, v0
	v_mov_b32_e32 v92, v0
	v_mov_b32_e32 v93, v0
	v_mov_b32_e32 v94, v0
	v_mov_b32_e32 v95, v0
	v_mov_b32_e32 v104, v0
	v_mov_b32_e32 v105, v0
	v_mov_b32_e32 v106, v0
	v_mov_b32_e32 v107, v0
	v_mov_b32_e32 v108, v0
	v_mov_b32_e32 v109, v0
	v_mov_b32_e32 v110, v0
	v_mov_b32_e32 v111, v0
	v_mov_b32_e32 v120, v0
	v_mov_b32_e32 v121, v0
	v_mov_b32_e32 v122, v0
	v_mov_b32_e32 v123, v0
	v_mov_b32_e32 v124, v0
	v_mov_b32_e32 v125, v0
	v_mov_b32_e32 v126, v0
	v_mov_b32_e32 v127, v0
	.p2align	6

; template <class Epi, bool ALIGN_EPI>
; __device__ __forceinline__ void gemm_phase(LAS unsigned char* lds, const Gemm g, const StaticOrder& S, const Epi& E) {
;     ...
;         const bool has_next = S.next(ui + 1, nxt);
;         const char* nA = has_next ? (const char*)g.A + (size_t)nxt.pm * tA + (size_t)nxt.pn * g.acol : cA; const char* nB = has_next ? (const char*)g.Bt + (size_t)nxt.pn * tB : cB;
;         for (int t = 0; t < nt; t += 2) {
;             const bool last = (t == nt - 2);
;             const char* a1 = cA + (size_t)(t + 1) * kstep;
;             const char* a2 = last ? nA : cA + (size_t)(t + 2) * kstep; const char* b2 = last ? nB : cB + (size_t)(t + 2) * kstep;
;             const char* a3 = a2 + kstep; const char* b3 = b2 + kstep;
;     ...
; #pragma unroll
;         for (int a = 0; a < 2; ++a)
; #pragma unroll
;             for (int b = 0; b < 2; ++b)
; #pragma unroll
;                 for (int m = 0; m < 4; ++m)
; #pragma unroll
;                     for (int n = 0; n < 2; ++n) acc[a][b][m][n] = (f32x4){0.f, 0.f, 0.f, 0.f};
.LBB0_1754:
	s_ashr_i32 s21, s20, 31
	s_lshl_b64 s[22:23], s[20:21], 22
	s_add_u32 s22, s33, s22
	s_addc_u32 s23, s36, s23
	s_and_b64 s[24:25], s[0:1], exec
	s_cselect_b32 s5, s23, s29
	s_cselect_b32 s21, s22, s28
	s_ashr_i32 s19, s18, 31
	s_lshl_b64 s[24:25], s[18:19], 22
	s_add_u32 s24, s2, s24
	s_addc_u32 s25, s3, s25
	s_and_b64 s[34:35], s[0:1], exec
	s_cselect_b32 s19, s25, s31
	s_cselect_b32 s48, s24, s30
	s_add_u32 s28, s28, 0x200080
	s_addc_u32 s29, s29, 0
	s_add_u32 s49, s30, 0x100
	v_mov_b32_e32 v0, 0
	s_addc_u32 s50, s31, 0
	s_mov_b32 s51, -2
	v_mov_b32_e32 v1, v0
	v_mov_b32_e32 v2, v0
	v_mov_b32_e32 v3, v0
	v_mov_b32_e32 v4, v0
	v_mov_b32_e32 v5, v0
	v_mov_b32_e32 v6, v0
	v_mov_b32_e32 v7, v0
	v_mov_b32_e32 v20, v0
	v_mov_b32_e32 v21, v0
	v_mov_b32_e32 v22, v0
	v_mov_b32_e32 v23, v0
	v_mov_b32_e32 v16, v0
	v_mov_b32_e32 v17, v0
	v_mov_b32_e32 v18, v0
	v_mov_b32_e32 v19, v0
	s_waitcnt vmcnt(0)
	v_mov_b32_e32 v36, v0
	v_mov_b32_e32 v37, v0
	v_mov_b32_e32 v38, v0
	v_mov_b32_e32 v39, v0
	v_mov_b32_e32 v32, v0
	v_mov_b32_e32 v33, v0
	v_mov_b32_e32 v34, v0
	v_mov_b32_e32 v35, v0
	v_mov_b32_e32 v52, v0
	v_mov_b32_e32 v53, v0
	v_mov_b32_e32 v54, v0
	v_mov_b32_e32 v55, v0
	v_mov_b32_e32 v48, v0
	v_mov_b32_e32 v49, v0
	v_mov_b32_e32 v50, v0
	v_mov_b32_e32 v51, v0
	v_mov_b32_e32 v12, v0
	v_mov_b32_e32 v13, v0
	v_mov_b32_e32 v14, v0
	v_mov_b32_e32 v15, v0
	v_mov_b32_e32 v8, v0
	v_mov_b32_e32 v9, v0
	v_mov_b32_e32 v10, v0
	v_mov_b32_e32 v11, v0
	v_mov_b32_e32 v28, v0
	v_mov_b32_e32 v29, v0
	v_mov_b32_e32 v30, v0
	v_mov_b32_e32 v31, v0
	v_mov_b32_e32 v24, v0
	v_mov_b32_e32 v25, v0
	v_mov_b32_e32 v26, v0
	v_mov_b32_e32 v27, v0
	v_mov_b32_e32 v44, v0
	v_mov_b32_e32 v45, v0
	v_mov_b32_e32 v46, v0
	v_mov_b32_e32 v47, v0
	v_mov_b32_e32 v40, v0
	v_mov_b32_e32 v41, v0
	v_mov_b32_e32 v42, v0
	v_mov_b32_e32 v43, v0
	v_mov_b32_e32 v60, v0
	v_mov_b32_e32 v61, v0
	v_mov_b32_e32 v62, v0
	v_mov_b32_e32 v63, v0
	v_mov_b32_e32 v56, v0
	v_mov_b32_e32 v57, v0
	v_mov_b32_e32 v58, v0
	v_mov_b32_e32 v59, v0
	v_mov_b32_e32 v68, v0
	v_mov_b32_e32 v69, v0
	v_mov_b32_e32 v70, v0
	v_mov_b32_e32 v71, v0
	v_mov_b32_e32 v64, v0
	v_mov_b32_e32 v65, v0
	v_mov_b32_e32 v66, v0
	v_mov_b32_e32 v67, v0
	v_mov_b32_e32 v84, v0
	v_mov_b32_e32 v85, v0
	v_mov_b32_e32 v86, v0
	v_mov_b32_e32 v87, v0
	v_mov_b32_e32 v80, v0
	v_mov_b32_e32 v81, v0
	v_mov_b32_e32 v82, v0
	v_mov_b32_e32 v83, v0
	v_mov_b32_e32 v100, v0
	v_mov_b32_e32 v101, v0
	v_mov_b32_e32 v102, v0
	v_mov_b32_e32 v103, v0
	v_mov_b32_e32 v96, v0
	v_mov_b32_e32 v97, v0
	v_mov_b32_e32 v98, v0
	v_mov_b32_e32 v99, v0
	v_mov_b32_e32 v116, v0
	v_mov_b32_e32 v117, v0
	v_mov_b32_e32 v118, v0
	v_mov_b32_e32 v119, v0
	v_mov_b32_e32 v112, v0
	v_mov_b32_e32 v113, v0
	v_mov_b32_e32 v114, v0
	v_mov_b32_e32 v115, v0
	v_mov_b32_e32 v76, v0
	v_mov_b32_e32 v77, v0
	v_mov_b32_e32 v78, v0
	v_mov_b32_e32 v79, v0
	v_mov_b32_e32 v72, v0
	v_mov_b32_e32 v73, v0
	v_mov_b32_e32 v74, v0
	v_mov_b32_e32 v75, v0
	v_mov_b32_e32 v92, v0
	v_mov_b32_e32 v93, v0
	v_mov_b32_e32 v94, v0
	v_mov_b32_e32 v95, v0
	v_mov_b32_e32 v88, v0
	v_mov_b32_e32 v89, v0
	v_mov_b32_e32 v90, v0
	v_mov_b32_e32 v91, v0
	v_mov_b32_e32 v108, v0
	v_mov_b32_e32 v109, v0
	v_mov_b32_e32 v110, v0
	v_mov_b32_e32 v111, v0
	v_mov_b32_e32 v104, v0
	v_mov_b32_e32 v105, v0
	v_mov_b32_e32 v106, v0
	v_mov_b32_e32 v107, v0
	v_mov_b32_e32 v124, v0
	v_mov_b32_e32 v125, v0
	v_mov_b32_e32 v126, v0
	v_mov_b32_e32 v127, v0
	v_mov_b32_e32 v120, v0
	v_mov_b32_e32 v121, v0
	v_mov_b32_e32 v122, v0
	v_mov_b32_e32 v123, v0
	.p2align	6
